# speedup vs baseline: 1.0396x; 1.0035x over previous
; DEV unsigned xb_ld(unsigned* p) { return __hip_atomic_load(p, __ATOMIC_RELAXED, __HIP_MEMORY_SCOPE_AGENT); }
; DEV unsigned xb_add(unsigned* p, unsigned v) { return __hip_atomic_fetch_add(p, v, __ATOMIC_RELAXED, __HIP_MEMORY_SCOPE_AGENT); }
; #define XB_SPIN(cond, bar) do { unsigned _sp = 0; while (cond) { __builtin_amdgcn_s_sleep(1); \
;     if ((++_sp & 255u) == 0u) { if (xb_ld(&(bar)[XB_TMO])) break; if (_sp > XB_SPIN_CAP) { atomicAdd(&(bar)[XB_TMO], 1u); break; } } } } while (0)
; #define GSYNC() xcd_barrier(p.xbar, s_xb)
; DEV void xcd_barrier(unsigned* bar, volatile unsigned* st) {
;   asm volatile("s_waitcnt vmcnt(0)" ::: "memory");
;   __syncthreads();
;   if (threadIdx.x == 0) {
;     XcdBarrier b; b.bar = bar; b.x = st[0]; b.nloc = st[1]; b.nx = st[2];
;     __builtin_amdgcn_s_waitcnt(0);
;     const unsigned old = xb_add(&bar[XB_XSUB(b.x)], 1u);
;     const unsigned gen = old / b.nloc;
;     if (old + 1u == (gen + 1u) * b.nloc) {
;       __builtin_amdgcn_fence(__ATOMIC_RELEASE, "agent");
;       asm volatile("s_waitcnt vmcnt(0)" ::: "memory");
;       const unsigned og = xb_add(&bar[XB_TOP], 1u);
;       const unsigned tg = og / b.nx;
;       if (og + 1u == (tg + 1u) * b.nx) xb_add(&bar[XB_TOPGEN], 1u);
;       else XB_SPIN(xb_ld(&bar[XB_TOPGEN]) == tg, bar);
;       __builtin_amdgcn_fence(__ATOMIC_ACQUIRE, "agent");
;       xb_add(&bar[XB_XGEN(b.x)], 1u);
;     } else {
;       XB_SPIN(xb_ld(&bar[XB_XGEN(b.x)]) == gen, bar);
;       __builtin_amdgcn_fence(__ATOMIC_ACQUIRE, "agent");
;     }
;   }
;   __syncthreads();
; }
; __global__ void __launch_bounds__(NTHREADS, 2) fwd_megakernel(Params p) {
;     ...
;       phase_plegate(p, layer, grp, smem);
;       GSYNC();
.LBB0_917:
	s_waitcnt vmcnt(0)
	s_barrier
	s_mov_b64 s[0:1], exec
	v_readlane_b32 s2, v254, 40
	v_readlane_b32 s3, v254, 41
	s_and_b64 s[2:3], s[0:1], s[2:3]
	s_mov_b64 exec, s[2:3]
	v_readlane_b32 s4, v255, 32
	v_readlane_b32 s5, v255, 33
	s_or_b32 s4, s4, s5
	s_cmp_eq_u32 s4, 0
	s_cbranch_scc1 .LBB0_321
	v_readlane_b32 s4, v255, 3
	s_cmp_lg_u32 s4, 3
	s_cbranch_scc1 .LBB0_321
	s_cbranch_execz .LBB0_321
	v_mov_b32_e32 v133, v141
	flat_load_dword v1, v[132:133] sc0 sc1
	s_waitcnt vmcnt(0)
	v_mov_b32_e32 v135, v141
	flat_load_dword v4, v[134:135] sc0 sc1
	s_waitcnt vmcnt(0)
	v_mov_b32_e32 v137, v141
	flat_load_dword v0, v[136:137] sc0 sc1
	s_waitcnt vmcnt(0) expcnt(0) lgkmcnt(0)
	v_lshlrev_b32_e32 v1, 6, v1
	v_add_u32_e32 v128, 0x500, v1
	v_lshl_add_u64 v[2:3], v[128:129], 2, s[28:29]
	global_atomic_add v3, v[2:3], v172, off sc0
	v_cvt_f32_u32_e32 v2, v4
	v_sub_u32_e32 v5, 0, v4
	v_add_u32_e32 v128, 0x900, v1
	v_rcp_iflag_f32_e32 v2, v2
	s_nop 0
	v_mul_f32_e32 v2, 0x4f7ffffe, v2
	v_cvt_u32_f32_e32 v2, v2
	v_mul_lo_u32 v5, v5, v2
	v_mul_hi_u32 v5, v2, v5
	v_add_u32_e32 v2, v2, v5
	s_waitcnt vmcnt(0)
	v_mul_hi_u32 v2, v3, v2
	v_mul_lo_u32 v5, v2, v4
	v_sub_u32_e32 v5, v3, v5
	v_cmp_ge_u32_e32 vcc, v5, v4
	v_add_u32_e32 v6, 1, v2
	v_add_u32_e32 v3, 1, v3
	v_cndmask_b32_e32 v2, v2, v6, vcc
	v_sub_u32_e32 v6, v5, v4
	v_cndmask_b32_e32 v5, v5, v6, vcc
	v_cmp_ge_u32_e32 vcc, v5, v4
	v_add_u32_e32 v5, 1, v2
	s_nop 0
	v_cndmask_b32_e32 v2, v2, v5, vcc
	v_mad_u64_u32 v[4:5], s[2:3], v4, v2, v[4:5]
	v_cmp_ne_u32_e32 vcc, v3, v4
	s_and_saveexec_b64 s[2:3], vcc
	s_xor_b64 s[2:3], exec, s[2:3]
	s_cbranch_execz .LBB0_951
	v_lshl_add_u64 v[0:1], v[128:129], 2, s[28:29]
	global_load_dword v3, v[0:1], off sc1
	s_waitcnt vmcnt(0)
	v_cmp_eq_u32_e32 vcc, v3, v2
	s_and_saveexec_b64 s[4:5], vcc
	s_cbranch_execz .LBB0_950
	s_mov_b32 s22, 1
	s_mov_b64 s[6:7], 0
	s_branch .LBB0_941
